# code placement: 4-byte phase of the z GEMM K-loop flipped (one s_nop 0 before the loop head, one after its back edge) so its 8-byte MFMA encodings start 8-byte aligned
# speedup vs baseline: 1.0003x; 1.0003x over previous
; #define PG8_STAGE(bufoff, gbase, voff) do { unsigned long long _gb = (unsigned long long)(gbase); asm volatile("" : "+s"(_gb)); _Pragma("unroll") for (int _i = 0; _i < 2; ++_i) \
;         __builtin_amdgcn_global_load_lds((const GAS unsigned*)((const GAS char*)_gb + (voff)[_i]), (LAS unsigned*)(lds + (bufoff) + ldsw + _i * 8192), 16, 0, 0); } while (0)
; #define PG8_WAIT_V(n) asm volatile("s_waitcnt vmcnt(" #n ")" ::: "memory")
; template <class Epi, bool ALIGN_EPI>
; __device__ __forceinline__ void gemm_phase(LAS unsigned char* lds, const Gemm g, const StaticOrder& S, const Epi& E, const int wid) {
;     ...
;     Unit cur, nxt; int ui = 0;
;     if (!S.next(0, cur)) return;
;     f32x4 acc[2][2][4][2];
; #pragma unroll
;     for (int a = 0; a < 2; ++a)
; #pragma unroll
;         for (int b = 0; b < 2; ++b)
; #pragma unroll
;             for (int m = 0; m < 4; ++m)
; #pragma unroll
;                 for (int n = 0; n < 2; ++n) acc[a][b][m][n] = (f32x4){0.f, 0.f, 0.f, 0.f};
;     bf16x8 At[4][2], B0[2][2], B1[2][2];
;     const char* cA = (const char*)g.A + (size_t)cur.pm * tstep; const char* cB = (const char*)g.Bt + (size_t)cur.pn * tstep;
;     PG8_STAGE(PG8_SB(0, 0), cB, voffB); PG8_STAGE(PG8_SB(0, 1), cB + hstepB, voffB); PG8_STAGE(PG8_SA(0, 0), cA, voffA); PG8_STAGE(PG8_SA(0, 1), cA + hstep, voffA);
;     if (wr == 1) PG8_BAR;
;     PG8_WAIT_V(2); PG8_BAR;
;     PG8_STAGE(PG8_SB(1, 0), cB + kstep, voffB); PG8_STAGE(PG8_SA(1, 0), cA + kstep, voffA); PG8_STAGE(PG8_SB(1, 1), cB + hstepB + kstep, voffB);
;     PG8_WAIT_V(6); PG8_BAR;
;     for (;;) {
;         const bool has_next = S.next(ui + 1, nxt);
;         const char* nA = has_next ? (const char*)g.A + (size_t)nxt.pm * tstep : cA; const char* nB = has_next ? (const char*)g.Bt + (size_t)nxt.pn * tstep : cB;
;         for (int t = 0; t < nt; t += 2) {
;             const bool last = (t == nt - 2);
;             const char* a1 = cA + (size_t)(t + 1) * kstep;
;             const char* a2 = last ? nA : cA + (size_t)(t + 2) * kstep; const char* b2 = last ? nB : cB + (size_t)(t + 2) * kstep;
;             const char* a3 = a2 + kstep; const char* b3 = b2 + kstep;
;             PG8_LDB(B0, 0, 0); PG8_LDB(B1, 0, 1); PG8_SCHED; PG8_LDA(At, 0, 0); PG8_STAGE(PG8_SA(1, 1), a1 + hstep, voffA);
;             PG8_WAIT_V(8); PG8_WAIT_L(0); PG8_BAR; PG8_MMA(0, 0, At, B0); PG8_MMA(0, 1, At, B1); PG8_BAR; PG8_SCHED;
.LBB0_104:
	s_ashr_i32 s39, s38, 31
	s_lshl_b64 s[40:41], s[38:39], 20
	s_add_u32 s40, s55, s40
	s_addc_u32 s41, s56, s41
	s_and_b64 s[42:43], s[4:5], exec
	s_cselect_b32 s39, s41, s3
	s_cselect_b32 s70, s40, s2
	s_ashr_i32 s37, s36, 31
	s_lshl_b64 s[42:43], s[36:37], 20
	s_add_u32 s42, s28, s42
	s_addc_u32 s43, s29, s43
	s_and_b64 s[48:49], s[4:5], exec
	s_cselect_b32 s37, s43, s7
	s_cselect_b32 s71, s42, s6
	s_add_u32 s72, s6, 0x100
	v_mov_b32_e32 v0, 0
	s_addc_u32 s73, s7, 0
	s_mov_b32 s74, -2
	v_mov_b32_e32 v1, v0
	v_mov_b32_e32 v2, v0
	v_mov_b32_e32 v3, v0
	v_mov_b32_e32 v4, v0
	v_mov_b32_e32 v5, v0
	v_mov_b32_e32 v6, v0
	v_mov_b32_e32 v7, v0
	v_mov_b32_e32 v16, v0
	v_mov_b32_e32 v17, v0
	v_mov_b32_e32 v18, v0
	v_mov_b32_e32 v19, v0
	v_mov_b32_e32 v20, v0
	v_mov_b32_e32 v21, v0
	v_mov_b32_e32 v22, v0
	v_mov_b32_e32 v23, v0
	v_mov_b32_e32 v32, v0
	v_mov_b32_e32 v33, v0
	v_mov_b32_e32 v34, v0
	v_mov_b32_e32 v35, v0
	v_mov_b32_e32 v36, v0
	v_mov_b32_e32 v37, v0
	v_mov_b32_e32 v38, v0
	v_mov_b32_e32 v39, v0
	v_mov_b32_e32 v48, v0
	v_mov_b32_e32 v49, v0
	v_mov_b32_e32 v50, v0
	v_mov_b32_e32 v51, v0
	v_mov_b32_e32 v52, v0
	v_mov_b32_e32 v53, v0
	v_mov_b32_e32 v54, v0
	v_mov_b32_e32 v55, v0
	v_mov_b32_e32 v8, v0
	v_mov_b32_e32 v9, v0
	v_mov_b32_e32 v10, v0
	v_mov_b32_e32 v11, v0
	v_mov_b32_e32 v12, v0
	v_mov_b32_e32 v13, v0
	v_mov_b32_e32 v14, v0
	v_mov_b32_e32 v15, v0
	v_mov_b32_e32 v24, v0
	v_mov_b32_e32 v25, v0
	v_mov_b32_e32 v26, v0
	v_mov_b32_e32 v27, v0
	v_mov_b32_e32 v28, v0
	v_mov_b32_e32 v29, v0
	v_mov_b32_e32 v30, v0
	v_mov_b32_e32 v31, v0
	v_mov_b32_e32 v40, v0
	v_mov_b32_e32 v41, v0
	v_mov_b32_e32 v42, v0
	v_mov_b32_e32 v43, v0
	v_mov_b32_e32 v44, v0
	v_mov_b32_e32 v45, v0
	v_mov_b32_e32 v46, v0
	v_mov_b32_e32 v47, v0
	v_mov_b32_e32 v56, v0
	v_mov_b32_e32 v57, v0
	v_mov_b32_e32 v58, v0
	v_mov_b32_e32 v59, v0
	v_mov_b32_e32 v60, v0
	v_mov_b32_e32 v61, v0
	v_mov_b32_e32 v62, v0
	v_mov_b32_e32 v63, v0
	v_mov_b32_e32 v64, v0
	v_mov_b32_e32 v65, v0
	v_mov_b32_e32 v66, v0
	v_mov_b32_e32 v67, v0
	v_mov_b32_e32 v68, v0
	v_mov_b32_e32 v69, v0
	v_mov_b32_e32 v70, v0
	v_mov_b32_e32 v71, v0
	v_mov_b32_e32 v80, v0
	v_mov_b32_e32 v81, v0
	v_mov_b32_e32 v82, v0
	v_mov_b32_e32 v83, v0
	v_mov_b32_e32 v84, v0
	v_mov_b32_e32 v85, v0
	v_mov_b32_e32 v86, v0
	v_mov_b32_e32 v87, v0
	v_mov_b32_e32 v96, v0
	v_mov_b32_e32 v97, v0
	v_mov_b32_e32 v98, v0
	v_mov_b32_e32 v99, v0
	v_mov_b32_e32 v100, v0
	v_mov_b32_e32 v101, v0
	v_mov_b32_e32 v102, v0
	v_mov_b32_e32 v103, v0
	v_mov_b32_e32 v112, v0
	v_mov_b32_e32 v113, v0
	v_mov_b32_e32 v114, v0
	v_mov_b32_e32 v115, v0
	v_mov_b32_e32 v116, v0
	v_mov_b32_e32 v117, v0
	v_mov_b32_e32 v118, v0
	v_mov_b32_e32 v119, v0
	v_mov_b32_e32 v72, v0
	v_mov_b32_e32 v73, v0
	v_mov_b32_e32 v74, v0
	v_mov_b32_e32 v75, v0
	v_mov_b32_e32 v76, v0
	v_mov_b32_e32 v77, v0
	v_mov_b32_e32 v78, v0
	v_mov_b32_e32 v79, v0
	v_mov_b32_e32 v88, v0
	v_mov_b32_e32 v89, v0
	v_mov_b32_e32 v90, v0
	v_mov_b32_e32 v91, v0
	v_mov_b32_e32 v92, v0
	v_mov_b32_e32 v93, v0
	v_mov_b32_e32 v94, v0
	v_mov_b32_e32 v95, v0
	v_mov_b32_e32 v104, v0
	v_mov_b32_e32 v105, v0
	v_mov_b32_e32 v106, v0
	v_mov_b32_e32 v107, v0
	v_mov_b32_e32 v108, v0
	v_mov_b32_e32 v109, v0
	v_mov_b32_e32 v110, v0
	v_mov_b32_e32 v111, v0
	v_mov_b32_e32 v120, v0
	v_mov_b32_e32 v121, v0
	v_mov_b32_e32 v122, v0
	v_mov_b32_e32 v123, v0
	v_mov_b32_e32 v124, v0
	v_mov_b32_e32 v125, v0
	v_mov_b32_e32 v126, v0
	v_mov_b32_e32 v127, v0
	s_nop 0
.LBB0_105:
	ds_read_b128 v[128:131], v204
	ds_read_b128 v[132:135], v204 offset:1024
	ds_read_b128 v[136:139], v204 offset:2048
	ds_read_b128 v[140:143], v204 offset:3072
	ds_read_b128 v[162:165], v205
	ds_read_b128 v[166:169], v205 offset:1024
	ds_read_b128 v[170:173], v205 offset:2048
	ds_read_b128 v[174:177], v205 offset:3072
	s_add_u32 s6, s2, 0x100
	s_addc_u32 s7, s3, 0
	s_cmp_eq_u32 s74, 28
	s_cselect_b32 s52, s70, s6
	s_cselect_b32 s53, s39, s7
	s_cselect_b32 s50, s71, s72
	s_cselect_b32 s51, s37, s73
	s_add_u32 s48, s52, 0x80
	s_addc_u32 s49, s53, 0
	s_add_u32 s2, s2, 0x80080
	s_addc_u32 s3, s3, 0
	ds_read_b128 v[178:181], v206
	ds_read_b128 v[186:189], v206 offset:1024
	ds_read_b128 v[190:193], v206 offset:2048
	ds_read_b128 v[194:197], v206 offset:3072
	ds_read_b128 v[198:201], v206 offset:4096
	ds_read_b128 v[210:213], v206 offset:5120
	ds_read_b128 v[214:217], v206 offset:6144
	s_add_i32 m0, s45, 0xc000
	ds_read_b128 v[218:221], v206 offset:7168
	global_load_lds_dwordx4 v144, s[2:3]
	s_add_i32 m0, s45, 0xe000
	s_nop 0
	global_load_lds_dwordx4 v148, s[2:3]
	s_waitcnt vmcnt(8) lgkmcnt(0)
	s_barrier
; #define PG8_STAGE(bufoff, gbase, voff) do { unsigned long long _gb = (unsigned long long)(gbase); asm volatile("" : "+s"(_gb)); _Pragma("unroll") for (int _i = 0; _i < 2; ++_i) \
;         __builtin_amdgcn_global_load_lds((const GAS unsigned*)((const GAS char*)_gb + (voff)[_i]), (LAS unsigned*)(lds + (bufoff) + ldsw + _i * 8192), 16, 0, 0); } while (0)
; #define PG8_LDA(dst, b, h) do { _Pragma("unroll") for (int m = 0; m < 4; ++m) _Pragma("unroll") for (int k = 0; k < 2; ++k) dst[m][k] = *(const LAS bf16x8*)(lds + PG8_SA(b, h) + aoff + m * 2048 + k * 1024); } while (0)
; #define PG8_MMA(ai, bj, At, Bt) do { __builtin_amdgcn_s_setprio(1); _Pragma("unroll") for (int m = 0; m < 4; ++m) _Pragma("unroll") for (int n = 0; n < 2; ++n) _Pragma("unroll") for (int k = 0; k < 2; ++k) \
;         acc[ai][bj][m][n] = __builtin_amdgcn_mfma_f32_16x16x32_bf16(Bt[n][k], At[m][k], acc[ai][bj][m][n], 0, 0, 0); __builtin_amdgcn_s_setprio(0); } while (0)
; #define PG8_WAIT_V(n) asm volatile("s_waitcnt vmcnt(" #n ")" ::: "memory")
; #define PG8_WAIT_L(n) asm volatile("s_waitcnt lgkmcnt(" #n ")" ::: "memory")
; #define PG8_BAR __builtin_amdgcn_s_barrier()
; #define PG8_SCHED __builtin_amdgcn_sched_barrier(0)
; template <class Epi, bool ALIGN_EPI>
; __device__ __forceinline__ void gemm_phase(LAS unsigned char* lds, const Gemm g, const StaticOrder& S, const Epi& E, const int wid) {
;     ...
;             PG8_WAIT_V(8); PG8_WAIT_L(0); PG8_BAR; PG8_MMA(0, 0, At, B0); PG8_MMA(0, 1, At, B1); PG8_BAR; PG8_SCHED;
;             PG8_LDA(At, 0, 1); PG8_STAGE(PG8_SB(0, 0), b2, voffB); PG8_STAGE(PG8_SB(0, 1), b2 + hstepB, voffB); PG8_STAGE(PG8_SA(0, 0), a2, voffA);
;             PG8_WAIT_V(8); PG8_WAIT_L(0); PG8_BAR; PG8_MMA(1, 0, At, B0); PG8_MMA(1, 1, At, B1); PG8_BAR; PG8_SCHED;
	s_setprio 1
	v_mfma_f32_16x16x32_bf16 v[124:127], v[128:131], v[178:181], v[124:127]
	v_mfma_f32_16x16x32_bf16 v[120:123], v[136:139], v[178:181], v[120:123]
	v_mfma_f32_16x16x32_bf16 v[108:111], v[128:131], v[190:193], v[108:111]
	v_mfma_f32_16x16x32_bf16 v[104:107], v[136:139], v[190:193], v[104:107]
	v_mfma_f32_16x16x32_bf16 v[92:95], v[128:131], v[198:201], v[92:95]
	v_mfma_f32_16x16x32_bf16 v[88:91], v[136:139], v[198:201], v[88:91]
	v_mfma_f32_16x16x32_bf16 v[76:79], v[128:131], v[214:217], v[76:79]
	v_mfma_f32_16x16x32_bf16 v[72:75], v[136:139], v[214:217], v[72:75]
	v_mfma_f32_16x16x32_bf16 v[124:127], v[132:135], v[186:189], v[124:127]
	v_mfma_f32_16x16x32_bf16 v[120:123], v[140:143], v[186:189], v[120:123]
	v_mfma_f32_16x16x32_bf16 v[108:111], v[132:135], v[194:197], v[108:111]
	v_mfma_f32_16x16x32_bf16 v[104:107], v[140:143], v[194:197], v[104:107]
	v_mfma_f32_16x16x32_bf16 v[92:95], v[132:135], v[210:213], v[92:95]
	v_mfma_f32_16x16x32_bf16 v[88:91], v[140:143], v[210:213], v[88:91]
	v_mfma_f32_16x16x32_bf16 v[76:79], v[132:135], v[218:221], v[76:79]
	v_mfma_f32_16x16x32_bf16 v[72:75], v[140:143], v[218:221], v[72:75]
	v_mfma_f32_16x16x32_bf16 v[116:119], v[162:165], v[178:181], v[116:119]
	v_mfma_f32_16x16x32_bf16 v[112:115], v[170:173], v[178:181], v[112:115]
	v_mfma_f32_16x16x32_bf16 v[100:103], v[162:165], v[190:193], v[100:103]
	v_mfma_f32_16x16x32_bf16 v[96:99], v[170:173], v[190:193], v[96:99]
	v_mfma_f32_16x16x32_bf16 v[84:87], v[162:165], v[198:201], v[84:87]
	v_mfma_f32_16x16x32_bf16 v[80:83], v[170:173], v[198:201], v[80:83]
	v_mfma_f32_16x16x32_bf16 v[68:71], v[162:165], v[214:217], v[68:71]
	v_mfma_f32_16x16x32_bf16 v[64:67], v[170:173], v[214:217], v[64:67]
	v_mfma_f32_16x16x32_bf16 v[116:119], v[166:169], v[186:189], v[116:119]
	v_mfma_f32_16x16x32_bf16 v[112:115], v[174:177], v[186:189], v[112:115]
	v_mfma_f32_16x16x32_bf16 v[100:103], v[166:169], v[194:197], v[100:103]
	v_mfma_f32_16x16x32_bf16 v[96:99], v[174:177], v[194:197], v[96:99]
	v_mfma_f32_16x16x32_bf16 v[84:87], v[166:169], v[210:213], v[84:87]
	v_mfma_f32_16x16x32_bf16 v[80:83], v[174:177], v[210:213], v[80:83]
	v_mfma_f32_16x16x32_bf16 v[68:71], v[166:169], v[218:221], v[68:71]
	v_mfma_f32_16x16x32_bf16 v[64:67], v[174:177], v[218:221], v[64:67]
	s_setprio 0
	s_barrier
	s_mov_b64 s[2:3], s[50:51]
	s_add_i32 s75, s66, s33
	ds_read_b128 v[178:181], v206 offset:16384
	ds_read_b128 v[186:189], v206 offset:17408
	ds_read_b128 v[190:193], v206 offset:18432
	ds_read_b128 v[194:197], v206 offset:19456
	ds_read_b128 v[198:201], v206 offset:20480
	ds_read_b128 v[210:213], v206 offset:21504
	ds_read_b128 v[214:217], v206 offset:22528
	s_mov_b32 m0, s75
	ds_read_b128 v[218:221], v206 offset:23552
	global_load_lds_dwordx4 v146, s[2:3]
	s_add_i32 m0, s75, 0x2000
	s_nop 0
	global_load_lds_dwordx4 v150, s[2:3]
	s_add_u32 s2, s50, 0x20000
	s_addc_u32 s3, s51, 0
	s_add_i32 s75, s67, s33
	s_mov_b32 m0, s75
	s_nop 0
	global_load_lds_dwordx4 v146, s[2:3]
	s_add_i32 m0, s75, 0x2000
	s_nop 0
	global_load_lds_dwordx4 v150, s[2:3]
	s_mov_b32 m0, s45
	s_mov_b64 s[2:3], s[52:53]
	global_load_lds_dwordx4 v144, s[2:3]
	s_mov_b32 m0, s47
	s_nop 0
	global_load_lds_dwordx4 v148, s[2:3]
	s_waitcnt vmcnt(8) lgkmcnt(0)
	s_barrier
	s_setprio 1
	v_mfma_f32_16x16x32_bf16 v[60:63], v[128:131], v[178:181], v[60:63]
	v_mfma_f32_16x16x32_bf16 v[56:59], v[136:139], v[178:181], v[56:59]
	v_mfma_f32_16x16x32_bf16 v[44:47], v[128:131], v[190:193], v[44:47]
	v_mfma_f32_16x16x32_bf16 v[40:43], v[136:139], v[190:193], v[40:43]
	v_mfma_f32_16x16x32_bf16 v[28:31], v[128:131], v[198:201], v[28:31]
	v_mfma_f32_16x16x32_bf16 v[24:27], v[136:139], v[198:201], v[24:27]
	v_mfma_f32_16x16x32_bf16 v[12:15], v[128:131], v[214:217], v[12:15]
	v_mfma_f32_16x16x32_bf16 v[8:11], v[136:139], v[214:217], v[8:11]
	v_mfma_f32_16x16x32_bf16 v[60:63], v[132:135], v[186:189], v[60:63]
	v_mfma_f32_16x16x32_bf16 v[56:59], v[140:143], v[186:189], v[56:59]
	v_mfma_f32_16x16x32_bf16 v[44:47], v[132:135], v[194:197], v[44:47]
	v_mfma_f32_16x16x32_bf16 v[40:43], v[140:143], v[194:197], v[40:43]
	v_mfma_f32_16x16x32_bf16 v[28:31], v[132:135], v[210:213], v[28:31]
	v_mfma_f32_16x16x32_bf16 v[24:27], v[140:143], v[210:213], v[24:27]
	v_mfma_f32_16x16x32_bf16 v[12:15], v[132:135], v[218:221], v[12:15]
	v_mfma_f32_16x16x32_bf16 v[8:11], v[140:143], v[218:221], v[8:11]
	v_mfma_f32_16x16x32_bf16 v[52:55], v[162:165], v[178:181], v[52:55]
	v_mfma_f32_16x16x32_bf16 v[48:51], v[170:173], v[178:181], v[48:51]
	v_mfma_f32_16x16x32_bf16 v[36:39], v[162:165], v[190:193], v[36:39]
	v_mfma_f32_16x16x32_bf16 v[32:35], v[170:173], v[190:193], v[32:35]
	v_mfma_f32_16x16x32_bf16 v[20:23], v[162:165], v[198:201], v[20:23]
	v_mfma_f32_16x16x32_bf16 v[16:19], v[170:173], v[198:201], v[16:19]
	v_mfma_f32_16x16x32_bf16 v[4:7], v[162:165], v[214:217], v[4:7]
	v_mfma_f32_16x16x32_bf16 v[0:3], v[170:173], v[214:217], v[0:3]
	v_mfma_f32_16x16x32_bf16 v[52:55], v[166:169], v[186:189], v[52:55]
	v_mfma_f32_16x16x32_bf16 v[48:51], v[174:177], v[186:189], v[48:51]
	v_mfma_f32_16x16x32_bf16 v[36:39], v[166:169], v[194:197], v[36:39]
	v_mfma_f32_16x16x32_bf16 v[32:35], v[174:177], v[194:197], v[32:35]
	v_mfma_f32_16x16x32_bf16 v[20:23], v[166:169], v[210:213], v[20:23]
	v_mfma_f32_16x16x32_bf16 v[16:19], v[174:177], v[210:213], v[16:19]
	v_mfma_f32_16x16x32_bf16 v[4:7], v[166:169], v[218:221], v[4:7]
	v_mfma_f32_16x16x32_bf16 v[0:3], v[174:177], v[218:221], v[0:3]
	s_setprio 0
	s_barrier
; #define PG8_STAGE(bufoff, gbase, voff) do { unsigned long long _gb = (unsigned long long)(gbase); asm volatile("" : "+s"(_gb)); _Pragma("unroll") for (int _i = 0; _i < 2; ++_i) \
;         __builtin_amdgcn_global_load_lds((const GAS unsigned*)((const GAS char*)_gb + (voff)[_i]), (LAS unsigned*)(lds + (bufoff) + ldsw + _i * 8192), 16, 0, 0); } while (0)
; #define PG8_LDA(dst, b, h) do { _Pragma("unroll") for (int m = 0; m < 4; ++m) _Pragma("unroll") for (int k = 0; k < 2; ++k) dst[m][k] = *(const LAS bf16x8*)(lds + PG8_SA(b, h) + aoff + m * 2048 + k * 1024); } while (0)
; #define PG8_LDB(dst, b, h) do { _Pragma("unroll") for (int n = 0; n < 2; ++n) _Pragma("unroll") for (int k = 0; k < 2; ++k) dst[n][k] = *(const LAS bf16x8*)(lds + PG8_SB(b, h) + boff + n * 2048 + k * 1024); } while (0)
; #define PG8_MMA(ai, bj, At, Bt) do { __builtin_amdgcn_s_setprio(1); _Pragma("unroll") for (int m = 0; m < 4; ++m) _Pragma("unroll") for (int n = 0; n < 2; ++n) _Pragma("unroll") for (int k = 0; k < 2; ++k) \
;         acc[ai][bj][m][n] = __builtin_amdgcn_mfma_f32_16x16x32_bf16(Bt[n][k], At[m][k], acc[ai][bj][m][n], 0, 0, 0); __builtin_amdgcn_s_setprio(0); } while (0)
; #define PG8_WAIT_V(n) asm volatile("s_waitcnt vmcnt(" #n ")" ::: "memory")
; #define PG8_WAIT_L(n) asm volatile("s_waitcnt lgkmcnt(" #n ")" ::: "memory")
; #define PG8_BAR __builtin_amdgcn_s_barrier()
; #define PG8_SCHED __builtin_amdgcn_sched_barrier(0)
; template <class Epi, bool ALIGN_EPI>
; __device__ __forceinline__ void gemm_phase(LAS unsigned char* lds, const Gemm g, const StaticOrder& S, const Epi& E, const int wid) {
;     ...
;             PG8_LDB(B0, 1, 0); PG8_LDB(B1, 1, 1); PG8_SCHED; PG8_LDA(At, 1, 0); PG8_STAGE(PG8_SA(0, 1), a2 + hstep, voffA);
;             PG8_WAIT_V(8); PG8_WAIT_L(0); PG8_BAR; PG8_MMA(0, 0, At, B0); PG8_MMA(0, 1, At, B1); PG8_BAR; PG8_SCHED;
;             PG8_LDA(At, 1, 1); PG8_STAGE(PG8_SB(1, 0), b3, voffB); PG8_STAGE(PG8_SB(1, 1), b3 + hstepB, voffB); PG8_STAGE(PG8_SA(1, 0), a3, voffA);
;             PG8_WAIT_V(8); PG8_WAIT_L(0); PG8_BAR; PG8_MMA(1, 0, At, B0); PG8_MMA(1, 1, At, B1); PG8_BAR; PG8_SCHED;
;         }
	s_add_i32 s75, 0, 0x18000
	s_add_i32 s76, 0, 0x1c000
	v_add_u32_e32 v140, s75, v203
	v_add_u32_e32 v152, s76, v203
	ds_read_b128 v[128:131], v140
	ds_read_b128 v[132:135], v140 offset:1024
	ds_read_b128 v[136:139], v140 offset:2048
	ds_read_b128 v[140:143], v140 offset:3072
	ds_read_b128 v[162:165], v152
	ds_read_b128 v[166:169], v152 offset:1024
	ds_read_b128 v[170:173], v152 offset:2048
	ds_read_b128 v[174:177], v152 offset:3072
	s_add_u32 s2, s52, 0x80000
	s_addc_u32 s3, s53, 0
	s_mov_b32 m0, s57
	ds_read_b128 v[178:181], v206 offset:32768
	ds_read_b128 v[186:189], v206 offset:33792
	ds_read_b128 v[190:193], v206 offset:34816
	ds_read_b128 v[194:197], v206 offset:35840
	ds_read_b128 v[198:201], v206 offset:36864
	ds_read_b128 v[210:213], v206 offset:37888
	ds_read_b128 v[214:217], v206 offset:38912
	ds_read_b128 v[218:221], v206 offset:39936
	s_nop 0
	global_load_lds_dwordx4 v144, s[2:3]
	s_mov_b32 m0, s58
	s_nop 0
	global_load_lds_dwordx4 v148, s[2:3]
	s_waitcnt vmcnt(8) lgkmcnt(0)
	s_barrier
	s_setprio 1
	v_mfma_f32_16x16x32_bf16 v[124:127], v[128:131], v[178:181], v[124:127]
	v_mfma_f32_16x16x32_bf16 v[120:123], v[136:139], v[178:181], v[120:123]
	v_mfma_f32_16x16x32_bf16 v[108:111], v[128:131], v[190:193], v[108:111]
	v_mfma_f32_16x16x32_bf16 v[104:107], v[136:139], v[190:193], v[104:107]
	v_mfma_f32_16x16x32_bf16 v[92:95], v[128:131], v[198:201], v[92:95]
	v_mfma_f32_16x16x32_bf16 v[88:91], v[136:139], v[198:201], v[88:91]
	v_mfma_f32_16x16x32_bf16 v[76:79], v[128:131], v[214:217], v[76:79]
	v_mfma_f32_16x16x32_bf16 v[72:75], v[136:139], v[214:217], v[72:75]
	v_mfma_f32_16x16x32_bf16 v[124:127], v[132:135], v[186:189], v[124:127]
	v_mfma_f32_16x16x32_bf16 v[120:123], v[140:143], v[186:189], v[120:123]
	v_mfma_f32_16x16x32_bf16 v[108:111], v[132:135], v[194:197], v[108:111]
	v_mfma_f32_16x16x32_bf16 v[104:107], v[140:143], v[194:197], v[104:107]
	v_mfma_f32_16x16x32_bf16 v[92:95], v[132:135], v[210:213], v[92:95]
	v_mfma_f32_16x16x32_bf16 v[88:91], v[140:143], v[210:213], v[88:91]
	v_mfma_f32_16x16x32_bf16 v[76:79], v[132:135], v[218:221], v[76:79]
	v_mfma_f32_16x16x32_bf16 v[72:75], v[140:143], v[218:221], v[72:75]
	v_mfma_f32_16x16x32_bf16 v[116:119], v[162:165], v[178:181], v[116:119]
	v_mfma_f32_16x16x32_bf16 v[112:115], v[170:173], v[178:181], v[112:115]
	v_mfma_f32_16x16x32_bf16 v[100:103], v[162:165], v[190:193], v[100:103]
	v_mfma_f32_16x16x32_bf16 v[96:99], v[170:173], v[190:193], v[96:99]
	v_mfma_f32_16x16x32_bf16 v[84:87], v[162:165], v[198:201], v[84:87]
	v_mfma_f32_16x16x32_bf16 v[80:83], v[170:173], v[198:201], v[80:83]
	v_mfma_f32_16x16x32_bf16 v[68:71], v[162:165], v[214:217], v[68:71]
	v_mfma_f32_16x16x32_bf16 v[64:67], v[170:173], v[214:217], v[64:67]
	v_mfma_f32_16x16x32_bf16 v[116:119], v[166:169], v[186:189], v[116:119]
	v_mfma_f32_16x16x32_bf16 v[112:115], v[174:177], v[186:189], v[112:115]
	v_mfma_f32_16x16x32_bf16 v[100:103], v[166:169], v[194:197], v[100:103]
	v_mfma_f32_16x16x32_bf16 v[96:99], v[174:177], v[194:197], v[96:99]
	v_mfma_f32_16x16x32_bf16 v[84:87], v[166:169], v[210:213], v[84:87]
	v_mfma_f32_16x16x32_bf16 v[80:83], v[174:177], v[210:213], v[80:83]
	v_mfma_f32_16x16x32_bf16 v[68:71], v[166:169], v[218:221], v[68:71]
	v_mfma_f32_16x16x32_bf16 v[64:67], v[174:177], v[218:221], v[64:67]
	s_setprio 0
	s_barrier
	s_add_u32 s2, s50, 0x80
	s_addc_u32 s3, s51, 0
	s_add_i32 s52, s75, s33
	ds_read_b128 v[178:181], v206 offset:49152
	ds_read_b128 v[186:189], v206 offset:50176
	ds_read_b128 v[190:193], v206 offset:51200
	ds_read_b128 v[194:197], v206 offset:52224
	ds_read_b128 v[198:201], v206 offset:53248
	ds_read_b128 v[210:213], v206 offset:54272
	ds_read_b128 v[214:217], v206 offset:55296
	s_mov_b32 m0, s52
	ds_read_b128 v[218:221], v206 offset:56320
	global_load_lds_dwordx4 v146, s[2:3]
	s_add_i32 m0, s52, 0x2000
	s_nop 0
	global_load_lds_dwordx4 v150, s[2:3]
	s_add_u32 s2, s50, 0x20080
	s_addc_u32 s3, s51, 0
	s_add_i32 s50, s76, s33
	s_mov_b32 m0, s50
	s_nop 0
	global_load_lds_dwordx4 v146, s[2:3]
	s_add_i32 m0, s50, 0x2000
	s_nop 0
	global_load_lds_dwordx4 v150, s[2:3]
	s_mov_b32 m0, s63
	s_nop 0
	global_load_lds_dwordx4 v144, s[48:49]
	s_mov_b32 m0, s64
	s_nop 0
	global_load_lds_dwordx4 v148, s[48:49]
	s_waitcnt vmcnt(8) lgkmcnt(0)
	s_barrier
	s_setprio 1
	v_mfma_f32_16x16x32_bf16 v[60:63], v[128:131], v[178:181], v[60:63]
	v_mfma_f32_16x16x32_bf16 v[56:59], v[136:139], v[178:181], v[56:59]
	v_mfma_f32_16x16x32_bf16 v[44:47], v[128:131], v[190:193], v[44:47]
	v_mfma_f32_16x16x32_bf16 v[40:43], v[136:139], v[190:193], v[40:43]
	v_mfma_f32_16x16x32_bf16 v[28:31], v[128:131], v[198:201], v[28:31]
	v_mfma_f32_16x16x32_bf16 v[24:27], v[136:139], v[198:201], v[24:27]
	v_mfma_f32_16x16x32_bf16 v[12:15], v[128:131], v[214:217], v[12:15]
	v_mfma_f32_16x16x32_bf16 v[8:11], v[136:139], v[214:217], v[8:11]
	v_mfma_f32_16x16x32_bf16 v[60:63], v[132:135], v[186:189], v[60:63]
	v_mfma_f32_16x16x32_bf16 v[56:59], v[140:143], v[186:189], v[56:59]
	v_mfma_f32_16x16x32_bf16 v[44:47], v[132:135], v[194:197], v[44:47]
	v_mfma_f32_16x16x32_bf16 v[40:43], v[140:143], v[194:197], v[40:43]
	v_mfma_f32_16x16x32_bf16 v[28:31], v[132:135], v[210:213], v[28:31]
	v_mfma_f32_16x16x32_bf16 v[24:27], v[140:143], v[210:213], v[24:27]
	v_mfma_f32_16x16x32_bf16 v[12:15], v[132:135], v[218:221], v[12:15]
	v_mfma_f32_16x16x32_bf16 v[8:11], v[140:143], v[218:221], v[8:11]
	v_mfma_f32_16x16x32_bf16 v[52:55], v[162:165], v[178:181], v[52:55]
	v_mfma_f32_16x16x32_bf16 v[48:51], v[170:173], v[178:181], v[48:51]
	v_mfma_f32_16x16x32_bf16 v[36:39], v[162:165], v[190:193], v[36:39]
	v_mfma_f32_16x16x32_bf16 v[32:35], v[170:173], v[190:193], v[32:35]
	v_mfma_f32_16x16x32_bf16 v[20:23], v[162:165], v[198:201], v[20:23]
	v_mfma_f32_16x16x32_bf16 v[16:19], v[170:173], v[198:201], v[16:19]
	v_mfma_f32_16x16x32_bf16 v[4:7], v[162:165], v[214:217], v[4:7]
	v_mfma_f32_16x16x32_bf16 v[0:3], v[170:173], v[214:217], v[0:3]
	v_mfma_f32_16x16x32_bf16 v[52:55], v[166:169], v[186:189], v[52:55]
	v_mfma_f32_16x16x32_bf16 v[48:51], v[174:177], v[186:189], v[48:51]
	v_mfma_f32_16x16x32_bf16 v[36:39], v[166:169], v[194:197], v[36:39]
	v_mfma_f32_16x16x32_bf16 v[32:35], v[174:177], v[194:197], v[32:35]
	v_mfma_f32_16x16x32_bf16 v[20:23], v[166:169], v[210:213], v[20:23]
	v_mfma_f32_16x16x32_bf16 v[16:19], v[174:177], v[210:213], v[16:19]
	v_mfma_f32_16x16x32_bf16 v[4:7], v[166:169], v[218:221], v[4:7]
	v_mfma_f32_16x16x32_bf16 v[0:3], v[174:177], v[218:221], v[0:3]
	s_setprio 0
	s_barrier
	s_add_i32 s74, s74, 2
	s_add_u32 s72, s72, 0x100
	s_addc_u32 s73, s73, 0
	s_cmp_gt_u32 s74, 29
	s_mov_b64 s[2:3], s[6:7]
	s_cbranch_scc0 .LBB0_105
	s_nop 0
	s_and_b64 vcc, exec, s[84:85]
	s_cbranch_vccz .LBB0_108
	s_barrier
